# combine phase: all 12 row loads of a token issued up front with counted waits
# speedup vs baseline: 1.0125x; 1.0015x over previous
.LBB0_695:
	v_lshl_add_u64 v[8:9], s[8:9], 0, v[96:97]
	v_add_co_u32_e32 v10, vcc, 0x4000000, v8
	global_load_dwordx4 v[16:19], v[8:9], off
	s_nop 0
	v_addc_co_u32_e32 v11, vcc, 0, v9, vcc
	global_load_dwordx4 v[20:23], v[10:11], off
	v_lshl_add_u64 v[24:25], s[6:7], 0, v[96:97]
	v_add_co_u32_e32 v28, vcc, 0x11000000, v24
	s_add_i32 s1, s1, s56
	s_nop 0
	v_addc_co_u32_e32 v29, vcc, 0, v25, vcc
	global_load_dwordx4 v[24:27], v[28:29], off
	s_add_u32 s6, s6, s10
	s_addc_u32 s7, s7, s11
	s_add_u32 s8, s8, s10
	s_addc_u32 s9, s9, s11
	s_cmpk_lt_i32 s1, 0x4000
	global_load_dwordx4 v[100:103], v[8:9], off offset:1024
	global_load_dwordx4 v[104:107], v[10:11], off offset:1024
	global_load_dwordx4 v[108:111], v[28:29], off offset:1024
	global_load_dwordx4 v[112:115], v[8:9], off offset:2048
	global_load_dwordx4 v[116:119], v[10:11], off offset:2048
	global_load_dwordx4 v[120:123], v[28:29], off offset:2048
	global_load_dwordx4 v[124:127], v[8:9], off offset:3072
	global_load_dwordx4 v[128:131], v[10:11], off offset:3072
	global_load_dwordx4 v[132:135], v[28:29], off offset:3072
	s_waitcnt vmcnt(11)
	v_lshlrev_b32_e32 v30, 16, v16
	v_and_b32_e32 v16, 0xffff0000, v16
	v_lshlrev_b32_e32 v33, 16, v17
	s_waitcnt vmcnt(10)
	v_lshlrev_b32_e32 v15, 16, v20
	v_add_f32_e32 v15, v15, v30
	v_and_b32_e32 v20, 0xffff0000, v20
	v_lshlrev_b32_e32 v31, 16, v21
	v_and_b32_e32 v30, 0xffff0000, v21
	v_and_b32_e32 v32, 0xffff0000, v17
	v_lshlrev_b32_e32 v35, 16, v23
	v_lshlrev_b32_e32 v37, 16, v19
	v_and_b32_e32 v34, 0xffff0000, v23
	v_and_b32_e32 v36, 0xffff0000, v19
	v_add_f32_e32 v38, v20, v16
	v_lshlrev_b32_e32 v21, 16, v18
	v_and_b32_e32 v20, 0xffff0000, v18
	v_pk_add_f32 v[18:19], v[32:33], v[30:31]
	v_pk_add_f32 v[30:31], v[36:37], v[34:35]
	v_mul_f32_e32 v34, v15, v15
	v_lshlrev_b32_e32 v17, 16, v22
	v_and_b32_e32 v16, 0xffff0000, v22
	v_pk_mul_f32 v[22:23], v[18:19], v[18:19]
	v_fmac_f32_e32 v34, v38, v38
	v_pk_add_f32 v[16:17], v[20:21], v[16:17]
	v_add_f32_e32 v23, v23, v34
	v_pk_mul_f32 v[20:21], v[16:17], v[16:17]
	v_add_f32_e32 v22, v22, v23
	v_add_f32_e32 v21, v21, v22
	v_pk_mul_f32 v[32:33], v[30:31], v[30:31]
	v_add_f32_e32 v20, v20, v21
	v_add_f32_e32 v20, v33, v20
	v_add_f32_e32 v20, v32, v20
	s_waitcnt vmcnt(9)
	v_and_b32_e32 v22, 0xffff0000, v24
	v_lshlrev_b32_e32 v23, 16, v25
	v_add_f32_dpp v20, v20, v20 quad_perm:[1,0,3,2] row_mask:0xf bank_mask:0xf bound_ctrl:1
	v_lshlrev_b32_e32 v32, 16, v27
	v_and_b32_e32 v27, 0xffff0000, v27
	v_add_f32_dpp v20, v20, v20 quad_perm:[2,3,0,1] row_mask:0xf bank_mask:0xf bound_ctrl:1
	s_nop 1
	v_add_f32_dpp v20, v20, v20 row_half_mirror row_mask:0xf bank_mask:0xf bound_ctrl:1
	s_nop 1
	v_add_f32_dpp v20, v20, v20 row_mirror row_mask:0xf bank_mask:0xf bound_ctrl:1
	v_fmamk_f32 v20, v20, 0x3c000000, v189
	v_cmp_gt_f32_e32 vcc, s2, v20
	v_mul_f32_e32 v21, 0x4b800000, v20
	s_nop 0
	v_cndmask_b32_e32 v20, v20, v21, vcc
	v_rsq_f32_e32 v20, v20
	s_nop 0
	v_mul_f32_e32 v21, 0x45800000, v20
	v_cndmask_b32_e32 v20, v20, v21, vcc
	v_mul_f32_e32 v19, v19, v20
	v_mul_f32_e32 v16, v16, v20
	v_lshlrev_b32_e32 v21, 16, v24
	v_and_b32_e32 v24, 0xffff0000, v25
	v_lshlrev_b32_e32 v25, 16, v26
	v_and_b32_e32 v26, 0xffff0000, v26
	v_mul_f32_e32 v19, v2, v19
	v_mul_f32_e32 v16, v5, v16
	v_mul_f32_e32 v15, v15, v20
	v_mul_f32_e32 v19, v19, v23
	v_mul_f32_e32 v18, v18, v20
	v_mul_f32_e32 v23, v16, v26
	v_mul_f32_e32 v16, v31, v20
	v_mul_f32_e32 v15, v0, v15
	v_mul_f32_e32 v18, v3, v18
	v_mul_f32_e32 v16, v6, v16
	v_mul_f32_e32 v15, v15, v21
	v_mul_f32_e32 v21, v38, v20
	v_mul_f32_e32 v18, v18, v24
	v_mul_f32_e32 v17, v17, v20
	v_mul_f32_e32 v24, v16, v32
	v_mul_f32_e32 v16, v30, v20
	v_mul_f32_e32 v21, v1, v21
	v_mul_f32_e32 v17, v4, v17
	v_mul_f32_e32 v16, v7, v16
	v_mul_f32_e32 v21, v21, v22
	v_mul_f32_e32 v22, v17, v25
	v_mul_f32_e32 v20, v16, v27
	v_cvt_pk_bf16_f32 v16, v15, v21
	v_cvt_pk_bf16_f32 v17, v19, v18
	v_cvt_pk_bf16_f32 v18, v22, v23
	v_cvt_pk_bf16_f32 v19, v24, v20
	global_store_dwordx4 v[8:9], v[16:19], off
	s_waitcnt vmcnt(9)
	v_lshlrev_b32_e32 v30, 16, v100
	s_waitcnt vmcnt(8)
	v_lshlrev_b32_e32 v15, 16, v104
	v_add_f32_e32 v15, v15, v30
	v_and_b32_e32 v104, 0xffff0000, v104
	v_and_b32_e32 v100, 0xffff0000, v100
	v_lshlrev_b32_e32 v31, 16, v105
	v_lshlrev_b32_e32 v33, 16, v101
	v_and_b32_e32 v30, 0xffff0000, v105
	v_and_b32_e32 v32, 0xffff0000, v101
	v_lshlrev_b32_e32 v35, 16, v107
	v_lshlrev_b32_e32 v37, 16, v103
	v_and_b32_e32 v34, 0xffff0000, v107
	v_and_b32_e32 v36, 0xffff0000, v103
	v_add_f32_e32 v38, v104, v100
	v_lshlrev_b32_e32 v105, 16, v102
	v_and_b32_e32 v104, 0xffff0000, v102
	v_pk_add_f32 v[102:103], v[32:33], v[30:31]
	v_pk_add_f32 v[30:31], v[36:37], v[34:35]
	v_mul_f32_e32 v34, v15, v15
	v_lshlrev_b32_e32 v101, 16, v106
	v_and_b32_e32 v100, 0xffff0000, v106
	v_pk_mul_f32 v[106:107], v[102:103], v[102:103]
	v_fmac_f32_e32 v34, v38, v38
	v_pk_add_f32 v[100:101], v[104:105], v[100:101]
	v_add_f32_e32 v107, v107, v34
	v_pk_mul_f32 v[104:105], v[100:101], v[100:101]
	v_add_f32_e32 v106, v106, v107
	v_add_f32_e32 v105, v105, v106
	v_pk_mul_f32 v[32:33], v[30:31], v[30:31]
	v_add_f32_e32 v104, v104, v105
	v_add_f32_e32 v104, v33, v104
	v_add_f32_e32 v104, v32, v104
	s_waitcnt vmcnt(7)
	v_and_b32_e32 v106, 0xffff0000, v108
	v_lshlrev_b32_e32 v107, 16, v109
	v_add_f32_dpp v104, v104, v104 quad_perm:[1,0,3,2] row_mask:0xf bank_mask:0xf bound_ctrl:1
	v_lshlrev_b32_e32 v32, 16, v111
	v_and_b32_e32 v111, 0xffff0000, v111
	v_add_f32_dpp v104, v104, v104 quad_perm:[2,3,0,1] row_mask:0xf bank_mask:0xf bound_ctrl:1
	s_nop 1
	v_add_f32_dpp v104, v104, v104 row_half_mirror row_mask:0xf bank_mask:0xf bound_ctrl:1
	s_nop 1
	v_add_f32_dpp v104, v104, v104 row_mirror row_mask:0xf bank_mask:0xf bound_ctrl:1
	v_fmamk_f32 v104, v104, 0x3c000000, v189
	v_cmp_gt_f32_e32 vcc, s2, v104
	v_mul_f32_e32 v105, 0x4b800000, v104
	s_nop 0
	v_cndmask_b32_e32 v104, v104, v105, vcc
	v_rsq_f32_e32 v104, v104
	s_nop 0
	v_mul_f32_e32 v105, 0x45800000, v104
	v_cndmask_b32_e32 v104, v104, v105, vcc
	v_mul_f32_e32 v103, v103, v104
	v_mul_f32_e32 v100, v100, v104
	v_lshlrev_b32_e32 v105, 16, v108
	v_and_b32_e32 v108, 0xffff0000, v109
	v_lshlrev_b32_e32 v109, 16, v110
	v_and_b32_e32 v110, 0xffff0000, v110
	v_mul_f32_e32 v103, v2, v103
	v_mul_f32_e32 v100, v5, v100
	v_mul_f32_e32 v15, v15, v104
	v_mul_f32_e32 v103, v103, v107
	v_mul_f32_e32 v102, v102, v104
	v_mul_f32_e32 v107, v100, v110
	v_mul_f32_e32 v100, v31, v104
	v_mul_f32_e32 v15, v0, v15
	v_mul_f32_e32 v102, v3, v102
	v_mul_f32_e32 v100, v6, v100
	v_mul_f32_e32 v15, v15, v105
	v_mul_f32_e32 v105, v38, v104
	v_mul_f32_e32 v102, v102, v108
	v_mul_f32_e32 v101, v101, v104
	v_mul_f32_e32 v108, v100, v32
	v_mul_f32_e32 v100, v30, v104
	v_mul_f32_e32 v105, v1, v105
	v_mul_f32_e32 v101, v4, v101
	v_mul_f32_e32 v100, v7, v100
	v_mul_f32_e32 v105, v105, v106
	v_mul_f32_e32 v106, v101, v109
	v_mul_f32_e32 v104, v100, v111
	v_cvt_pk_bf16_f32 v100, v15, v105
	v_cvt_pk_bf16_f32 v101, v103, v102
	v_cvt_pk_bf16_f32 v102, v106, v107
	v_cvt_pk_bf16_f32 v103, v108, v104
	global_store_dwordx4 v[8:9], v[100:103], off offset:1024
	s_waitcnt vmcnt(7)
	v_lshlrev_b32_e32 v30, 16, v112
	s_waitcnt vmcnt(6)
	v_lshlrev_b32_e32 v15, 16, v116
	v_add_f32_e32 v15, v15, v30
	v_and_b32_e32 v116, 0xffff0000, v116
	v_and_b32_e32 v112, 0xffff0000, v112
	v_lshlrev_b32_e32 v31, 16, v117
	v_lshlrev_b32_e32 v33, 16, v113
	v_and_b32_e32 v30, 0xffff0000, v117
	v_and_b32_e32 v32, 0xffff0000, v113
	v_lshlrev_b32_e32 v35, 16, v119
	v_lshlrev_b32_e32 v37, 16, v115
	v_and_b32_e32 v34, 0xffff0000, v119
	v_and_b32_e32 v36, 0xffff0000, v115
	v_add_f32_e32 v38, v116, v112
	v_lshlrev_b32_e32 v117, 16, v114
	v_and_b32_e32 v116, 0xffff0000, v114
	v_pk_add_f32 v[114:115], v[32:33], v[30:31]
	v_pk_add_f32 v[30:31], v[36:37], v[34:35]
	v_mul_f32_e32 v34, v15, v15
	v_lshlrev_b32_e32 v113, 16, v118
	v_and_b32_e32 v112, 0xffff0000, v118
	v_pk_mul_f32 v[118:119], v[114:115], v[114:115]
	v_fmac_f32_e32 v34, v38, v38
	v_pk_add_f32 v[112:113], v[116:117], v[112:113]
	v_add_f32_e32 v119, v119, v34
	v_pk_mul_f32 v[116:117], v[112:113], v[112:113]
	v_add_f32_e32 v118, v118, v119
	v_add_f32_e32 v117, v117, v118
	v_pk_mul_f32 v[32:33], v[30:31], v[30:31]
	v_add_f32_e32 v116, v116, v117
	v_add_f32_e32 v116, v33, v116
	v_add_f32_e32 v116, v32, v116
	s_waitcnt vmcnt(5)
	v_and_b32_e32 v118, 0xffff0000, v120
	v_lshlrev_b32_e32 v119, 16, v121
	v_add_f32_dpp v116, v116, v116 quad_perm:[1,0,3,2] row_mask:0xf bank_mask:0xf bound_ctrl:1
	v_lshlrev_b32_e32 v32, 16, v123
	v_and_b32_e32 v123, 0xffff0000, v123
	v_add_f32_dpp v116, v116, v116 quad_perm:[2,3,0,1] row_mask:0xf bank_mask:0xf bound_ctrl:1
	s_nop 1
	v_add_f32_dpp v116, v116, v116 row_half_mirror row_mask:0xf bank_mask:0xf bound_ctrl:1
	s_nop 1
	v_add_f32_dpp v116, v116, v116 row_mirror row_mask:0xf bank_mask:0xf bound_ctrl:1
	v_fmamk_f32 v116, v116, 0x3c000000, v189
	v_cmp_gt_f32_e32 vcc, s2, v116
	v_mul_f32_e32 v117, 0x4b800000, v116
	s_nop 0
	v_cndmask_b32_e32 v116, v116, v117, vcc
	v_rsq_f32_e32 v116, v116
	s_nop 0
	v_mul_f32_e32 v117, 0x45800000, v116
	v_cndmask_b32_e32 v116, v116, v117, vcc
	v_mul_f32_e32 v115, v115, v116
	v_mul_f32_e32 v112, v112, v116
	v_lshlrev_b32_e32 v117, 16, v120
	v_and_b32_e32 v120, 0xffff0000, v121
	v_lshlrev_b32_e32 v121, 16, v122
	v_and_b32_e32 v122, 0xffff0000, v122
	v_mul_f32_e32 v115, v2, v115
	v_mul_f32_e32 v112, v5, v112
	v_mul_f32_e32 v15, v15, v116
	v_mul_f32_e32 v115, v115, v119
	v_mul_f32_e32 v114, v114, v116
	v_mul_f32_e32 v119, v112, v122
	v_mul_f32_e32 v112, v31, v116
	v_mul_f32_e32 v15, v0, v15
	v_mul_f32_e32 v114, v3, v114
	v_mul_f32_e32 v112, v6, v112
	v_mul_f32_e32 v15, v15, v117
	v_mul_f32_e32 v117, v38, v116
	v_mul_f32_e32 v114, v114, v120
	v_mul_f32_e32 v113, v113, v116
	v_mul_f32_e32 v120, v112, v32
	v_mul_f32_e32 v112, v30, v116
	v_mul_f32_e32 v117, v1, v117
	v_mul_f32_e32 v113, v4, v113
	v_mul_f32_e32 v112, v7, v112
	v_mul_f32_e32 v117, v117, v118
	v_mul_f32_e32 v118, v113, v121
	v_mul_f32_e32 v116, v112, v123
	v_cvt_pk_bf16_f32 v112, v15, v117
	v_cvt_pk_bf16_f32 v113, v115, v114
	v_cvt_pk_bf16_f32 v114, v118, v119
	v_cvt_pk_bf16_f32 v115, v120, v116
	global_store_dwordx4 v[8:9], v[112:115], off offset:2048
	s_waitcnt vmcnt(5)
	v_lshlrev_b32_e32 v11, 16, v124
	s_waitcnt vmcnt(4)
	v_lshlrev_b32_e32 v10, 16, v128
	v_add_f32_e32 v15, v10, v11
	v_and_b32_e32 v10, 0xffff0000, v128
	v_and_b32_e32 v11, 0xffff0000, v124
	v_add_f32_e32 v34, v10, v11
	v_lshlrev_b32_e32 v11, 16, v129
	v_lshlrev_b32_e32 v29, 16, v125
	v_and_b32_e32 v10, 0xffff0000, v129
	v_and_b32_e32 v28, 0xffff0000, v125
	v_lshlrev_b32_e32 v31, 16, v131
	v_lshlrev_b32_e32 v33, 16, v127
	v_and_b32_e32 v30, 0xffff0000, v131
	v_and_b32_e32 v32, 0xffff0000, v127
	v_lshlrev_b32_e32 v125, 16, v130
	v_and_b32_e32 v124, 0xffff0000, v130
	v_pk_add_f32 v[10:11], v[28:29], v[10:11]
	v_pk_add_f32 v[130:131], v[32:33], v[30:31]
	v_mul_f32_e32 v30, v15, v15
	v_lshlrev_b32_e32 v129, 16, v126
	v_and_b32_e32 v128, 0xffff0000, v126
	v_pk_mul_f32 v[126:127], v[10:11], v[10:11]
	v_fmac_f32_e32 v30, v34, v34
	v_pk_add_f32 v[124:125], v[128:129], v[124:125]
	v_add_f32_e32 v127, v127, v30
	v_pk_mul_f32 v[128:129], v[124:125], v[124:125]
	v_add_f32_e32 v126, v126, v127
	v_add_f32_e32 v126, v129, v126
	v_pk_mul_f32 v[28:29], v[130:131], v[130:131]
	v_add_f32_e32 v126, v128, v126
	v_add_f32_e32 v126, v29, v126
	v_add_f32_e32 v126, v28, v126
	s_waitcnt vmcnt(3)
	v_and_b32_e32 v128, 0xffff0000, v132
	v_lshlrev_b32_e32 v129, 16, v133
	v_add_f32_dpp v126, v126, v126 quad_perm:[1,0,3,2] row_mask:0xf bank_mask:0xf bound_ctrl:1
	v_lshlrev_b32_e32 v28, 16, v135
	v_and_b32_e32 v135, 0xffff0000, v135
	v_add_f32_dpp v126, v126, v126 quad_perm:[2,3,0,1] row_mask:0xf bank_mask:0xf bound_ctrl:1
	s_nop 1
	v_add_f32_dpp v126, v126, v126 row_half_mirror row_mask:0xf bank_mask:0xf bound_ctrl:1
	s_nop 1
	v_add_f32_dpp v126, v126, v126 row_mirror row_mask:0xf bank_mask:0xf bound_ctrl:1
	v_fmamk_f32 v126, v126, 0x3c000000, v189
	v_cmp_gt_f32_e32 vcc, s2, v126
	v_mul_f32_e32 v127, 0x4b800000, v126
	s_nop 0
	v_cndmask_b32_e32 v126, v126, v127, vcc
	v_rsq_f32_e32 v126, v126
	s_nop 0
	v_mul_f32_e32 v127, 0x45800000, v126
	v_cndmask_b32_e32 v126, v126, v127, vcc
	v_mul_f32_e32 v11, v11, v126
	v_mul_f32_e32 v124, v124, v126
	v_lshlrev_b32_e32 v127, 16, v132
	v_and_b32_e32 v132, 0xffff0000, v133
	v_lshlrev_b32_e32 v133, 16, v134
	v_and_b32_e32 v134, 0xffff0000, v134
	v_mul_f32_e32 v15, v15, v126
	v_mul_f32_e32 v11, v2, v11
	v_mul_f32_e32 v124, v5, v124
	v_mul_f32_e32 v15, v0, v15
	v_mul_f32_e32 v11, v11, v129
	v_mul_f32_e32 v129, v124, v134
	v_mul_f32_e32 v124, v131, v126
	v_mul_f32_e32 v15, v15, v127
	v_mul_f32_e32 v127, v34, v126
	v_mul_f32_e32 v124, v6, v124
	v_mul_f32_e32 v127, v1, v127
	v_mul_f32_e32 v10, v10, v126
	v_mul_f32_e32 v125, v125, v126
	v_mul_f32_e32 v131, v124, v28
	v_mul_f32_e32 v124, v130, v126
	v_mul_f32_e32 v127, v127, v128
	v_mul_f32_e32 v10, v3, v10
	v_mul_f32_e32 v125, v4, v125
	v_mul_f32_e32 v124, v7, v124
	v_mul_f32_e32 v10, v10, v132
	v_mul_f32_e32 v128, v125, v133
	v_mul_f32_e32 v130, v124, v135
	v_cvt_pk_bf16_f32 v124, v15, v127
	v_cvt_pk_bf16_f32 v125, v11, v10
	v_cvt_pk_bf16_f32 v126, v128, v129
	v_cvt_pk_bf16_f32 v127, v131, v130
	global_store_dwordx4 v[8:9], v[124:127], off offset:3072
	s_cbranch_scc1 .LBB0_695
	v_readlane_b32 s60, v248, 9
	v_readlane_b32 s62, v248, 12
	v_readlane_b32 s64, v248, 14
	v_readlane_b32 s68, v248, 16
	v_readlane_b32 s70, v248, 18
	v_readlane_b32 s61, v248, 10
	v_readlane_b32 s63, v248, 13
	v_readlane_b32 s65, v248, 15
	v_readlane_b32 s69, v248, 17
	v_readlane_b32 s71, v248, 19
	v_readlane_b32 s67, v248, 23
	v_readlane_b32 s72, v248, 24
	v_readlane_b32 s73, v248, 25
